# grid-barrier poll loops without s_sleep
# baseline (speedup 1.0000x reference)
; __device__ __forceinline__ unsigned xb_ld(unsigned* p)              { return __hip_atomic_load(p, __ATOMIC_RELAXED, __HIP_MEMORY_SCOPE_AGENT); }
; __device__ __forceinline__ void xcd_barrier_complete(unsigned* bar, unsigned x, unsigned& nloc, unsigned& nx) {
;     const unsigned G = gridDim.x * gridDim.y * gridDim.z;
;     unsigned sum, cnt, mine, sp = 0u;
;     for (;;) {
;         sum = 0u; cnt = 0u; mine = 0u;
; #pragma unroll
;         for (unsigned j = 0; j < 16; ++j) { const unsigned c = xb_ld(&bar[XB_XCNT(j)]); sum += c; cnt += (c > 0u) ? 1u : 0u; mine = (j == x) ? c : mine; }
;         if (sum == G) break;
;         __builtin_amdgcn_s_sleep(1);
;         if ((++sp & 255u) == 0u) { if (xb_ld(&bar[XB_TMO])) break; if (sp > XB_SPIN_CAP) { atomicAdd(&bar[XB_TMO], 1u); break; } }
;     }
;     nloc = mine > 0u ? mine : 1u; nx = cnt > 0u ? cnt : 1u;
; }
.LBB0_14:
	v_readlane_b32 s2, v251, 16
	v_readlane_b32 s3, v251, 17
	v_readlane_b32 s4, v252, 58
	s_mov_b64 s[6:7], -1
	s_waitcnt lgkmcnt(0)
	s_nop 1
	global_load_dword v0, v145, s[2:3] sc1
	v_readlane_b32 s2, v251, 18
	v_readlane_b32 s3, v251, 19
	s_nop 4
	global_load_dword v1, v145, s[2:3] sc1
	v_readlane_b32 s2, v251, 20
	v_readlane_b32 s3, v251, 21
	s_waitcnt vmcnt(0)
	v_add_u32_e32 v16, v1, v0
	s_nop 2
	global_load_dword v2, v145, s[2:3] sc1
	v_readlane_b32 s2, v251, 22
	v_readlane_b32 s3, v251, 23
	s_waitcnt vmcnt(0)
	v_add_u32_e32 v16, v16, v2
	s_nop 2
	global_load_dword v3, v145, s[2:3] sc1
	v_readlane_b32 s2, v251, 24
	v_readlane_b32 s3, v251, 25
	s_waitcnt vmcnt(0)
	v_add_u32_e32 v16, v16, v3
	s_nop 2
	global_load_dword v4, v145, s[2:3] sc1
	v_readlane_b32 s2, v251, 26
	v_readlane_b32 s3, v251, 27
	s_waitcnt vmcnt(0)
	v_add_u32_e32 v16, v16, v4
	s_nop 2
	global_load_dword v5, v145, s[2:3] sc1
	v_readlane_b32 s2, v251, 28
	v_readlane_b32 s3, v251, 29
	s_waitcnt vmcnt(0)
	v_add_u32_e32 v16, v16, v5
	s_nop 2
	global_load_dword v6, v145, s[2:3] sc1
	v_readlane_b32 s2, v251, 30
	v_readlane_b32 s3, v251, 31
	s_waitcnt vmcnt(0)
	v_add_u32_e32 v16, v16, v6
	s_nop 2
	global_load_dword v7, v145, s[2:3] sc1
	v_readlane_b32 s2, v251, 32
	v_readlane_b32 s3, v251, 33
	s_waitcnt vmcnt(0)
	v_add_u32_e32 v16, v16, v7
	s_nop 2
	global_load_dword v8, v145, s[2:3] sc1
	v_readlane_b32 s2, v251, 34
	v_readlane_b32 s3, v251, 35
	s_waitcnt vmcnt(0)
	v_add_u32_e32 v16, v16, v8
	s_nop 2
	global_load_dword v9, v145, s[2:3] sc1
	v_readlane_b32 s2, v251, 36
	v_readlane_b32 s3, v251, 37
	s_waitcnt vmcnt(0)
	v_add_u32_e32 v16, v16, v9
	s_nop 2
	global_load_dword v10, v145, s[2:3] sc1
	v_readlane_b32 s2, v251, 38
	v_readlane_b32 s3, v251, 39
	s_waitcnt vmcnt(0)
	v_add_u32_e32 v16, v16, v10
	s_nop 2
	global_load_dword v11, v145, s[2:3] sc1
	v_readlane_b32 s2, v251, 40
	v_readlane_b32 s3, v251, 41
	s_waitcnt vmcnt(0)
	v_add_u32_e32 v16, v16, v11
	s_nop 2
	global_load_dword v12, v145, s[2:3] sc1
	v_readlane_b32 s2, v251, 42
	v_readlane_b32 s3, v251, 43
	s_waitcnt vmcnt(0)
	v_add_u32_e32 v16, v16, v12
	s_nop 2
	global_load_dword v13, v145, s[2:3] sc1
	v_readlane_b32 s2, v251, 44
	v_readlane_b32 s3, v251, 45
	s_waitcnt vmcnt(0)
	v_add_u32_e32 v16, v16, v13
	s_nop 2
	global_load_dword v14, v145, s[2:3] sc1
	v_readlane_b32 s2, v251, 46
	v_readlane_b32 s3, v251, 47
	s_waitcnt vmcnt(0)
	v_add_u32_e32 v16, v16, v14
	s_nop 2
	global_load_dword v15, v145, s[2:3] sc1
	s_mov_b64 s[2:3], -1
	s_waitcnt vmcnt(0)
	v_add_u32_e32 v16, v16, v15
	v_cmp_eq_u32_e32 vcc, s4, v16
	s_cbranch_vccnz .LBB0_13
	s_and_b32 s2, s13, 0xff
	s_cmp_eq_u32 s2, 0
	s_mov_b64 s[2:3], -1
	s_mov_b64 s[8:9], -1
	s_cbranch_scc0 .LBB0_18
	v_readlane_b32 s2, v251, 14
	v_readlane_b32 s3, v251, 15
	s_nop 4
	global_load_dword v16, v145, s[2:3] sc1
	s_waitcnt vmcnt(0)
	v_cmp_eq_u32_e32 vcc, 0, v16
	s_cbranch_vccnz .LBB0_20
	s_mov_b64 s[8:9], 0
	s_mov_b64 s[2:3], -1

; __device__ __forceinline__ unsigned xb_ld(unsigned* p)              { return __hip_atomic_load(p, __ATOMIC_RELAXED, __HIP_MEMORY_SCOPE_AGENT); }
; __device__ __forceinline__ unsigned xb_add(unsigned* p, unsigned v) { return __hip_atomic_fetch_add(p, v, __ATOMIC_RELAXED, __HIP_MEMORY_SCOPE_AGENT); }
; #define XB_SPIN(cond, bar) do { unsigned _sp = 0; while (cond) { __builtin_amdgcn_s_sleep(1); \
;     if ((++_sp & 255u) == 0u) { if (xb_ld(&(bar)[XB_TMO])) break; if (_sp > XB_SPIN_CAP) { atomicAdd(&(bar)[XB_TMO], 1u); break; } } } } while (0)
; __device__ __forceinline__ void xcd_barrier(const XcdBarrier& b, int tid) {
;     ...
;             else XB_SPIN(xb_ld(&bar[XB_TOPGEN]) == tg, bar);
;             __builtin_amdgcn_fence(__ATOMIC_ACQUIRE, "agent");
;             xb_add(&bar[XB_XGEN(b.x)], 1u);
;             asm volatile("s_waitcnt vmcnt(0)" ::: "memory");
;         } else {
;             XB_SPIN(xb_ld(&bar[XB_XGEN(b.x)]) == gen, bar);
.LBB0_32:
	s_and_b32 s18, s13, 0xff
	s_mov_b64 s[34:35], -1
	s_cmp_lg_u32 s18, 0
	s_mov_b64 s[38:39], -1
	s_cbranch_scc1 .LBB0_35
	v_readlane_b32 s4, v251, 14
	v_readlane_b32 s5, v251, 15
	s_nop 4
	global_load_dword v0, v145, s[4:5] sc1
	s_waitcnt vmcnt(0)
	v_cmp_eq_u32_e32 vcc, 0, v0
	s_cbranch_vccnz .LBB0_37
	s_mov_b64 s[38:39], 0
	s_mov_b64 s[36:37], -1

; __global__ void __launch_bounds__(512, 2) mk_fwd(Args a) {
;     ...
;         if (ph > a.ph_lo) { if (ph == a.ph_lo + 1) grid.sync(); else xcd_barrier(xbar, (int)threadIdx.x); }
.LBB0_72:
	global_load_dword v1, v145, s[2:3] offset:32 sc1
	s_waitcnt vmcnt(0)
	v_and_b32_e32 v1, 0xffff0000, v1
	v_cmp_ne_u32_e32 vcc, v1, v0
	s_or_b64 s[6:7], vcc, s[6:7]
	s_andn2_b64 exec, exec, s[6:7]
	s_cbranch_execnz .LBB0_72
